# baseline (speedup 1.0000x reference)
; template <int NP>
; __device__ __forceinline__ void row_scales(const float* part, int rowbase, int lane, float inv_dim, float (&rs)[2][4]) {
;     float v[2];
; #pragma unroll
;     for (int a = 0; a < 2; ++a) {
;         const f32x4* p = (const f32x4*)(part + (size_t)(rowbase + 128 * a + lane) * NP);
;         float s = 0.f;
; #pragma unroll
;         for (int i = 0; i < NP / 4; ++i) { const f32x4 t = p[i]; s += (t[0] + t[1]) + (t[2] + t[3]); }
;         v[a] = rsqrtf(s * inv_dim + 1e-6f);
;     }
;     const int fr = lane & 15;
; #pragma unroll
;     for (int a = 0; a < 2; ++a)
; #pragma unroll
;         for (int m = 0; m < 4; ++m) rs[a][m] = __shfl(v[a], m * 16 + fr);
; }
.LBB0_203:
	s_add_u32 s44, s38, 0x1b100000
	s_addc_u32 s45, s39, 0
	s_lshl_b32 s37, s37, 5
	s_and_b32 s37, s37, 0x60
	s_add_i32 m0, s41, 0x18000
	v_lshl_add_u64 v[6:7], v[6:7], 0, s[28:29]
	s_lshl_b32 s67, s46, 6
	s_lshl_b32 s1, s46, 13
	s_lshl_b32 s48, s37, 7
	v_and_b32_e32 v197, 15, v201
	v_lshl_add_u32 v174, s0, 8, v197
	v_add_u32_e32 v174, s67, v174
	v_and_b32_e32 v175, 48, v201
	v_lshl_or_b32 v174, v174, 7, v175
	v_mov_b32_e32 v175, 0
	v_lshl_add_u64 v[174:175], s[44:45], 0, v[174:175]
	s_mov_b64 s[100:101], 0x1000
	v_lshl_add_u64 v[194:195], v[174:175], 0, s[100:101]
	s_mov_b64 s[100:101], 0x4000
	v_lshl_add_u64 v[216:217], v[174:175], 0, s[100:101]
	v_lshl_add_u64 v[250:251], v[194:195], 0, s[100:101]
	global_load_dwordx4 v[130:133], v[174:175], off
	global_load_dwordx4 v[134:137], v[174:175], off offset:64
	global_load_dwordx4 v[138:141], v[174:175], off offset:2048
	global_load_dwordx4 v[166:169], v[174:175], off offset:2112
	global_load_dwordx4 v[170:173], v[194:195], off
	global_load_dwordx4 v[182:185], v[194:195], off offset:64
	global_load_dwordx4 v[186:189], v[194:195], off offset:2048
	global_load_dwordx4 v[190:193], v[194:195], off offset:2112
	global_load_dwordx4 v[208:211], v[216:217], off
	global_load_dwordx4 v[212:215], v[216:217], off offset:64
	global_load_dwordx4 v[226:229], v[216:217], off offset:2048
	global_load_dwordx4 v[230:233], v[216:217], off offset:2112
	global_load_dwordx4 v[234:237], v[250:251], off
	global_load_dwordx4 v[238:241], v[250:251], off offset:64
	global_load_dwordx4 v[242:245], v[250:251], off offset:2048
	global_load_dwordx4 v[246:249], v[250:251], off offset:2112
	v_lshrrev_b32_e32 v196, 6, v201
	v_lshlrev_b32_e32 v196, 9, v196
	v_lshl_or_b32 v196, v197, 5, v196
	v_add_u32_e32 v196, 0x20000, v196
	s_waitcnt vmcnt(0)
	v_pk_add_f32 v[130:131], v[130:131], v[132:133]
	v_pk_add_f32 v[134:135], v[134:135], v[136:137]
	v_pk_add_f32 v[138:139], v[138:139], v[140:141]
	v_pk_add_f32 v[166:167], v[166:167], v[168:169]
	v_pk_add_f32 v[170:171], v[170:171], v[172:173]
	v_pk_add_f32 v[182:183], v[182:183], v[184:185]
	v_pk_add_f32 v[186:187], v[186:187], v[188:189]
	v_pk_add_f32 v[190:191], v[190:191], v[192:193]
	v_pk_add_f32 v[208:209], v[208:209], v[210:211]
	v_pk_add_f32 v[212:213], v[212:213], v[214:215]
	v_pk_add_f32 v[226:227], v[226:227], v[228:229]
	v_pk_add_f32 v[230:231], v[230:231], v[232:233]
	v_pk_add_f32 v[234:235], v[234:235], v[236:237]
	v_pk_add_f32 v[238:239], v[238:239], v[240:241]
	v_pk_add_f32 v[242:243], v[242:243], v[244:245]
	v_pk_add_f32 v[246:247], v[246:247], v[248:249]
	v_pk_add_f32 v[130:131], v[130:131], v[134:135]
	v_pk_add_f32 v[138:139], v[138:139], v[166:167]
	v_pk_add_f32 v[170:171], v[170:171], v[182:183]
	v_pk_add_f32 v[186:187], v[186:187], v[190:191]
	v_pk_add_f32 v[208:209], v[208:209], v[212:213]
	v_pk_add_f32 v[226:227], v[226:227], v[230:231]
	v_pk_add_f32 v[234:235], v[234:235], v[238:239]
	v_pk_add_f32 v[242:243], v[242:243], v[246:247]
	v_add_f32_e32 v130, v130, v131
	v_add_f32_e32 v138, v138, v139
	v_add_f32_e32 v170, v170, v171
	v_add_f32_e32 v186, v186, v187
	v_add_f32_e32 v208, v208, v209
	v_add_f32_e32 v226, v226, v227
	v_add_f32_e32 v234, v234, v235
	v_add_f32_e32 v242, v242, v243
	v_mov_b32_e32 v132, v130
	v_mov_b32_e32 v140, v138
	v_mov_b32_e32 v172, v170
	v_mov_b32_e32 v188, v186
	v_mov_b32_e32 v210, v208
	v_mov_b32_e32 v228, v226
	v_mov_b32_e32 v236, v234
	v_mov_b32_e32 v244, v242
	v_permlane16_swap_b32_e32 v132, v130
	v_permlane16_swap_b32_e32 v140, v138
	v_permlane16_swap_b32_e32 v172, v170
	v_permlane16_swap_b32_e32 v188, v186
	v_permlane16_swap_b32_e32 v210, v208
	v_permlane16_swap_b32_e32 v228, v226
	v_permlane16_swap_b32_e32 v236, v234
	v_permlane16_swap_b32_e32 v244, v242
	v_add_f32_e32 v130, v130, v132
	v_add_f32_e32 v138, v138, v140
	v_add_f32_e32 v170, v170, v172
	v_add_f32_e32 v186, v186, v188
	v_add_f32_e32 v208, v208, v210
	v_add_f32_e32 v226, v226, v228
	v_add_f32_e32 v234, v234, v236
	v_add_f32_e32 v242, v242, v244
	v_mov_b32_e32 v132, v130
	v_mov_b32_e32 v140, v138
	v_mov_b32_e32 v172, v170
	v_mov_b32_e32 v188, v186
	v_mov_b32_e32 v210, v208
	v_mov_b32_e32 v228, v226
	v_mov_b32_e32 v236, v234
	v_mov_b32_e32 v244, v242
	v_permlane32_swap_b32_e32 v132, v130
	v_permlane32_swap_b32_e32 v140, v138
	v_permlane32_swap_b32_e32 v172, v170
	v_permlane32_swap_b32_e32 v188, v186
	v_permlane32_swap_b32_e32 v210, v208
	v_permlane32_swap_b32_e32 v228, v226
	v_permlane32_swap_b32_e32 v236, v234
	v_permlane32_swap_b32_e32 v244, v242
	v_add_f32_e32 v130, v130, v132
	v_add_f32_e32 v138, v138, v140
	v_add_f32_e32 v170, v170, v172
	v_add_f32_e32 v186, v186, v188
	v_add_f32_e32 v208, v208, v210
	v_add_f32_e32 v226, v226, v228
	v_add_f32_e32 v234, v234, v236
	v_add_f32_e32 v242, v242, v244
	v_fmamk_f32 v130, v130, 0x3a000000, v198
	v_fmamk_f32 v138, v138, 0x3a000000, v198
	v_fmamk_f32 v170, v170, 0x3a000000, v198
	v_fmamk_f32 v186, v186, 0x3a000000, v198
	v_fmamk_f32 v208, v208, 0x3a000000, v198
	v_fmamk_f32 v226, v226, 0x3a000000, v198
	v_fmamk_f32 v234, v234, 0x3a000000, v198
	v_fmamk_f32 v242, v242, 0x3a000000, v198
	v_rsq_f32_e32 v130, v130
	v_rsq_f32_e32 v138, v138
	v_rsq_f32_e32 v170, v170
	v_rsq_f32_e32 v186, v186
	v_rsq_f32_e32 v208, v208
	v_rsq_f32_e32 v226, v226
	v_rsq_f32_e32 v234, v234
	v_rsq_f32_e32 v242, v242
	s_add_i32 s98, s0, 1
	ds_write_b32 v196, v130
	ds_write_b32 v196, v138 offset:4
	ds_write_b32 v196, v170 offset:8
	ds_write_b32 v196, v186 offset:12
	ds_write_b32 v196, v208 offset:16
	ds_write_b32 v196, v226 offset:20
	ds_write_b32 v196, v234 offset:24
	ds_write_b32 v196, v242 offset:28
	s_waitcnt vmcnt(2)
	s_barrier
; #define PG8_STAGE(bufoff, gbase, voff) do { _Pragma("unroll") for (int _i = 0; _i < 2; ++_i) \
;         __builtin_amdgcn_global_load_lds((const unsigned*)((const char*)(gbase) + (voff)[_i]), (LAS unsigned*)(lds + (bufoff) + ldsw + _i * 8192), 16, 0, 0); } while (0)
; #define PG8_WAIT_V(n) asm volatile("s_waitcnt vmcnt(" #n ")" ::: "memory")
; #define PG8_BAR __builtin_amdgcn_s_barrier()
; template <class Epi, class Sched, bool HN = false>
; __device__ __forceinline__ void gemm_phase(LAS unsigned char* lds, const Gemm g, const Sched& S, const Epi& E) {
;     ...
;     for (int i = 0; i < 2; ++i) { int R, C; stage_rc(tid * 16 + i * 8192, R, C); const int Rb = Epi::PERM ? ((R & ~31) + perm32(R & 31)) : R;
;         voffA[i] = (unsigned)(R * K + C) * 2u; voffB[i] = (unsigned)(Rb * K + C) * 2u; }
;     const size_t kstep = (size_t)(BK * 2);
;     const size_t hstep = (size_t)HALF * K * 2;
;     const size_t tstep = 2 * hstep;
;     const unsigned ldsw = (unsigned)wid * 1024u;
;     const int aoff = lds_byte(wr * 64 + fr, fq * 8), boff = lds_byte(wc * 32 + fr, fq * 8);
;     ...
;     PG8_STAGE(PG8_SB(0, 0), cB, voffB); if constexpr (!HN) PG8_STAGE(PG8_SB(0, 1), cB + hstep, voffB); PG8_STAGE(PG8_SA(0, 0), cA, voffA); PG8_STAGE(PG8_SA(0, 1), cA + hstep, voffA);
;     if (wr == 1) PG8_BAR;
;     PG8_WAIT_V(2); PG8_BAR;
;     PG8_STAGE(PG8_SB(1, 0), cB + kstep, voffB); PG8_STAGE(PG8_SA(1, 0), cA + kstep, voffA); if constexpr (!HN) PG8_STAGE(PG8_SB(1, 1), cB + hstep + kstep, voffB);
;     if constexpr (HN) PG8_WAIT_V(4); else PG8_WAIT_V(6);
;     PG8_BAR;
	global_load_lds_dwordx4 v[6:7], off
	v_lshl_add_u64 v[4:5], v[4:5], 0, s[28:29]
	s_add_i32 m0, s41, 0x1a000
	s_add_i32 s70, s41, 0x8000
	s_add_i32 s71, s41, 0xa000
	global_load_lds_dwordx4 v[4:5], off
	v_lshl_add_u64 v[0:1], v[0:1], 0, s[28:29]
	s_mov_b32 m0, s70
	s_add_u32 s46, s56, 0x80080
	global_load_lds_dwordx4 v[0:1], off
	v_lshl_add_u64 v[0:1], v[2:3], 0, s[28:29]
	s_mov_b32 m0, s71
	s_addc_u32 s47, s57, 0
	global_load_lds_dwordx4 v[0:1], off
	s_add_i32 m0, s41, 0x1c000
	v_lshl_add_u64 v[0:1], s[46:47], 0, v[144:145]
	global_load_lds_dwordx4 v[0:1], off
	v_lshl_add_u64 v[0:1], s[46:47], 0, v[148:149]
	s_add_i32 m0, s41, 0x1e000
	v_and_b32_e32 v176, 15, v8
	global_load_lds_dwordx4 v[0:1], off
	v_lshrrev_b32_e32 v0, 1, v8
	v_and_b32_e32 v0, 24, v0
	v_or_b32_e32 v150, s37, v0
	v_lshlrev_b32_e32 v1, 1, v0
	v_lshlrev_b32_e32 v2, 2, v8
	v_lshlrev_b32_e32 v24, 1, v150
	v_lshl_or_b32 v1, v176, 6, v1
	v_and_b32_e32 v2, 32, v2
	v_lshl_add_u64 v[152:153], s[24:25], 0, v[24:25]
	v_lshl_add_u64 v[154:155], s[22:23], 0, v[24:25]
	v_lshlrev_b32_e32 v24, 5, v176
	v_bitop3_b32 v3, v1, s1, v2 bitop3:0xde
	v_bitop3_b32 v177, v1, s48, v2 bitop3:0xde
	v_lshl_add_u64 v[0:1], s[2:3], 0, v[24:25]
	v_and_b32_e32 v24, 16, v8
	v_lshl_add_u64 v[156:157], v[0:1], 0, v[24:25]
	v_lshlrev_b32_e32 v0, 15, v9
	v_and_b32_e32 v0, 0xffff0000, v0
	v_lshl_add_u32 v0, v10, 12, v0
	v_and_b32_e32 v1, 1, v9
	v_lshl_or_b32 v0, v1, 6, v0
	v_lshl_add_u32 v162, v11, 1, v0
	v_lshlrev_b32_e32 v0, 15, v12
	v_and_b32_e32 v0, 0xffff0000, v0
	v_lshl_add_u32 v0, v13, 12, v0
	v_and_b32_e32 v1, 1, v12
	s_waitcnt vmcnt(6)
	v_or_b32_e32 v178, 0x80, v150
	v_lshl_or_b32 v0, v1, 6, v0
	s_cmpk_lt_u32 s36, 0x100
	v_lshlrev_b32_e32 v24, 1, v178
	v_lshl_add_u32 v164, v14, 1, v0
	v_and_or_b32 v0, v218, 64, v176
	v_and_b32_e32 v151, 63, v8
	s_cselect_b64 s[46:47], -1, 0
	s_ashr_i32 s72, s60, 31
	v_lshl_add_u64 v[158:159], s[24:25], 0, v[24:25]
	v_lshl_add_u64 v[160:161], s[22:23], 0, v[24:25]
	v_mov_b32_e32 v163, v25
	v_mov_b32_e32 v165, v25
	s_mov_b32 s73, 0
	v_add_u32_e32 v179, 0, v3
	v_lshlrev_b32_e32 v180, 2, v0
	s_barrier
	s_branch .LBB0_206

; template <int NP>
; __device__ __forceinline__ void row_scales(const float* part, int rowbase, int lane, float inv_dim, float (&rs)[2][4]) {
;     float v[2];
; #pragma unroll
;     for (int a = 0; a < 2; ++a) {
;         const f32x4* p = (const f32x4*)(part + (size_t)(rowbase + 128 * a + lane) * NP);
;         float s = 0.f;
; #pragma unroll
;         for (int i = 0; i < NP / 4; ++i) { const f32x4 t = p[i]; s += (t[0] + t[1]) + (t[2] + t[3]); }
;         v[a] = rsqrtf(s * inv_dim + 1e-6f);
;     }
;     const int fr = lane & 15;
; #pragma unroll
;     for (int a = 0; a < 2; ++a)
; #pragma unroll
;         for (int m = 0; m < 4; ++m) rs[a][m] = __shfl(v[a], m * 16 + fr);
; }
.LBB0_1261:
	v_lshrrev_b32_e32 v15, 1, v14
	v_and_b32_e32 v15, 24, v15
	s_add_u32 s34, s22, 0x1b100000
	v_and_b32_e32 v162, 63, v14
	v_and_b32_e32 v163, 15, v14
	v_lshlrev_b32_e32 v16, 1, v15
	v_lshlrev_b32_e32 v14, 2, v14
	s_sext_i32_i16 s65, s0
	s_addc_u32 s35, s23, 0
	v_lshl_or_b32 v16, v163, 6, v16
	s_lshl_b32 s0, s43, 13
	v_and_b32_e32 v14, 32, v14
	v_bitop3_b32 v17, v16, s0, v14 bitop3:0xde
	s_lshl_b32 s0, s1, 5
	s_and_b32 s39, s0, 0x60
	s_add_i32 m0, s57, 0x18000
	v_lshl_add_u64 v[6:7], v[6:7], 0, s[28:29]
	s_lshl_b32 s61, s43, 6
	s_lshl_b32 s0, s39, 7
	v_lshl_add_u32 v160, s38, 8, v163
	v_add_u32_e32 v160, s61, v160
	v_and_b32_e32 v161, 48, v162
	v_lshl_or_b32 v160, v160, 7, v161
	v_mov_b32_e32 v161, 0
	v_lshl_add_u64 v[160:161], s[34:35], 0, v[160:161]
	s_mov_b64 s[100:101], 0x1000
	v_lshl_add_u64 v[196:197], v[160:161], 0, s[100:101]
	s_mov_b64 s[100:101], 0x4000
	v_lshl_add_u64 v[206:207], v[160:161], 0, s[100:101]
	v_lshl_add_u64 v[216:217], v[196:197], 0, s[100:101]
	global_load_dwordx4 v[130:133], v[160:161], off
	global_load_dwordx4 v[134:137], v[160:161], off offset:64
	global_load_dwordx4 v[138:141], v[160:161], off offset:2048
	global_load_dwordx4 v[152:155], v[160:161], off offset:2112
	global_load_dwordx4 v[156:159], v[196:197], off
	global_load_dwordx4 v[168:171], v[196:197], off offset:64
	global_load_dwordx4 v[172:175], v[196:197], off offset:2048
	global_load_dwordx4 v[176:179], v[196:197], off offset:2112
	global_load_dwordx4 v[180:183], v[206:207], off
	global_load_dwordx4 v[184:187], v[206:207], off offset:64
	global_load_dwordx4 v[188:191], v[206:207], off offset:2048
	global_load_dwordx4 v[192:195], v[206:207], off offset:2112
	global_load_dwordx4 v[208:211], v[216:217], off
	global_load_dwordx4 v[212:215], v[216:217], off offset:64
	global_load_dwordx4 v[226:229], v[216:217], off offset:2048
	global_load_dwordx4 v[230:233], v[216:217], off offset:2112
	v_lshrrev_b32_e32 v234, 6, v201
	v_and_b32_e32 v235, 15, v201
	v_lshlrev_b32_e32 v234, 9, v234
	v_lshl_or_b32 v234, v235, 5, v234
	v_add_u32_e32 v234, 0x20000, v234
	s_waitcnt vmcnt(0)
	v_pk_add_f32 v[130:131], v[130:131], v[132:133]
	v_pk_add_f32 v[134:135], v[134:135], v[136:137]
	v_pk_add_f32 v[138:139], v[138:139], v[140:141]
	v_pk_add_f32 v[152:153], v[152:153], v[154:155]
	v_pk_add_f32 v[156:157], v[156:157], v[158:159]
	v_pk_add_f32 v[168:169], v[168:169], v[170:171]
	v_pk_add_f32 v[172:173], v[172:173], v[174:175]
	v_pk_add_f32 v[176:177], v[176:177], v[178:179]
	v_pk_add_f32 v[180:181], v[180:181], v[182:183]
	v_pk_add_f32 v[184:185], v[184:185], v[186:187]
	v_pk_add_f32 v[188:189], v[188:189], v[190:191]
	v_pk_add_f32 v[192:193], v[192:193], v[194:195]
	v_pk_add_f32 v[208:209], v[208:209], v[210:211]
	v_pk_add_f32 v[212:213], v[212:213], v[214:215]
	v_pk_add_f32 v[226:227], v[226:227], v[228:229]
	v_pk_add_f32 v[230:231], v[230:231], v[232:233]
	v_pk_add_f32 v[130:131], v[130:131], v[134:135]
	v_pk_add_f32 v[138:139], v[138:139], v[152:153]
	v_pk_add_f32 v[156:157], v[156:157], v[168:169]
	v_pk_add_f32 v[172:173], v[172:173], v[176:177]
	v_pk_add_f32 v[180:181], v[180:181], v[184:185]
	v_pk_add_f32 v[188:189], v[188:189], v[192:193]
	v_pk_add_f32 v[208:209], v[208:209], v[212:213]
	v_pk_add_f32 v[226:227], v[226:227], v[230:231]
	v_add_f32_e32 v130, v130, v131
	v_add_f32_e32 v138, v138, v139
	v_add_f32_e32 v156, v156, v157
	v_add_f32_e32 v172, v172, v173
	v_add_f32_e32 v180, v180, v181
	v_add_f32_e32 v188, v188, v189
	v_add_f32_e32 v208, v208, v209
	v_add_f32_e32 v226, v226, v227
	v_mov_b32_e32 v132, v130
	v_mov_b32_e32 v140, v138
	v_mov_b32_e32 v158, v156
	v_mov_b32_e32 v174, v172
	v_mov_b32_e32 v182, v180
	v_mov_b32_e32 v190, v188
	v_mov_b32_e32 v210, v208
	v_mov_b32_e32 v228, v226
	v_permlane16_swap_b32_e32 v132, v130
	v_permlane16_swap_b32_e32 v140, v138
	v_permlane16_swap_b32_e32 v158, v156
	v_permlane16_swap_b32_e32 v174, v172
	v_permlane16_swap_b32_e32 v182, v180
	v_permlane16_swap_b32_e32 v190, v188
	v_permlane16_swap_b32_e32 v210, v208
	v_permlane16_swap_b32_e32 v228, v226
	v_add_f32_e32 v130, v130, v132
	v_add_f32_e32 v138, v138, v140
	v_add_f32_e32 v156, v156, v158
	v_add_f32_e32 v172, v172, v174
	v_add_f32_e32 v180, v180, v182
	v_add_f32_e32 v188, v188, v190
	v_add_f32_e32 v208, v208, v210
	v_add_f32_e32 v226, v226, v228
	v_mov_b32_e32 v132, v130
	v_mov_b32_e32 v140, v138
	v_mov_b32_e32 v158, v156
	v_mov_b32_e32 v174, v172
	v_mov_b32_e32 v182, v180
	v_mov_b32_e32 v190, v188
	v_mov_b32_e32 v210, v208
	v_mov_b32_e32 v228, v226
	v_permlane32_swap_b32_e32 v132, v130
	v_permlane32_swap_b32_e32 v140, v138
	v_permlane32_swap_b32_e32 v158, v156
	v_permlane32_swap_b32_e32 v174, v172
	v_permlane32_swap_b32_e32 v182, v180
	v_permlane32_swap_b32_e32 v190, v188
	v_permlane32_swap_b32_e32 v210, v208
	v_permlane32_swap_b32_e32 v228, v226
	v_add_f32_e32 v130, v130, v132
	v_add_f32_e32 v138, v138, v140
	v_add_f32_e32 v156, v156, v158
	v_add_f32_e32 v172, v172, v174
	v_add_f32_e32 v180, v180, v182
	v_add_f32_e32 v188, v188, v190
	v_add_f32_e32 v208, v208, v210
	v_add_f32_e32 v226, v226, v228
	v_fmamk_f32 v130, v130, 0x3a000000, v198
	v_fmamk_f32 v138, v138, 0x3a000000, v198
	v_fmamk_f32 v156, v156, 0x3a000000, v198
	v_fmamk_f32 v172, v172, 0x3a000000, v198
	v_fmamk_f32 v180, v180, 0x3a000000, v198
	v_fmamk_f32 v188, v188, 0x3a000000, v198
	v_fmamk_f32 v208, v208, 0x3a000000, v198
	v_fmamk_f32 v226, v226, 0x3a000000, v198
	v_rsq_f32_e32 v152, v130
	v_rsq_f32_e32 v154, v138
	v_rsq_f32_e32 v156, v156
	v_rsq_f32_e32 v140, v172
	v_rsq_f32_e32 v138, v180
	v_rsq_f32_e32 v136, v188
	v_rsq_f32_e32 v134, v208
	v_rsq_f32_e32 v130, v226
	s_add_i32 s98, s38, 1
	ds_write_b32 v234, v152
	ds_write_b32 v234, v154 offset:4
	ds_write_b32 v234, v156 offset:8
	ds_write_b32 v234, v140 offset:12
	ds_write_b32 v234, v138 offset:16
	ds_write_b32 v234, v136 offset:20
	ds_write_b32 v234, v134 offset:24
	ds_write_b32 v234, v130 offset:28
	s_waitcnt vmcnt(2)
	s_barrier
; #define PG8_STAGE(bufoff, gbase, voff) do { _Pragma("unroll") for (int _i = 0; _i < 2; ++_i) \
;         __builtin_amdgcn_global_load_lds((const unsigned*)((const char*)(gbase) + (voff)[_i]), (LAS unsigned*)(lds + (bufoff) + ldsw + _i * 8192), 16, 0, 0); } while (0)
; #define PG8_WAIT_V(n) asm volatile("s_waitcnt vmcnt(" #n ")" ::: "memory")
; #define PG8_BAR __builtin_amdgcn_s_barrier()
; template <class Epi, class Sched, bool HN = false>
; __device__ __forceinline__ void gemm_phase(LAS unsigned char* lds, const Gemm g, const Sched& S, const Epi& E) {
;     ...
;     PG8_STAGE(PG8_SB(0, 0), cB, voffB); if constexpr (!HN) PG8_STAGE(PG8_SB(0, 1), cB + hstep, voffB); PG8_STAGE(PG8_SA(0, 0), cA, voffA); PG8_STAGE(PG8_SA(0, 1), cA + hstep, voffA);
;     if (wr == 1) PG8_BAR;
;     PG8_WAIT_V(2); PG8_BAR;
;     PG8_STAGE(PG8_SB(1, 0), cB + kstep, voffB); PG8_STAGE(PG8_SA(1, 0), cA + kstep, voffA); if constexpr (!HN) PG8_STAGE(PG8_SB(1, 1), cB + hstep + kstep, voffB);
;     if constexpr (HN) PG8_WAIT_V(4); else PG8_WAIT_V(6);
;     PG8_BAR;
	global_load_lds_dwordx4 v[6:7], off
	v_lshl_add_u64 v[4:5], v[4:5], 0, s[28:29]
	s_add_i32 m0, s57, 0x1a000
	s_add_i32 s62, s57, 0x8000
	s_add_i32 s63, s57, 0xa000
	v_bitop3_b32 v164, v16, s0, v14 bitop3:0xde
	global_load_lds_dwordx4 v[4:5], off
	v_lshl_add_u64 v[0:1], v[0:1], 0, s[28:29]
	s_mov_b32 m0, s62
	s_add_u32 s0, s52, 0x80080
	global_load_lds_dwordx4 v[0:1], off
	v_lshl_add_u64 v[0:1], v[2:3], 0, s[28:29]
	s_mov_b32 m0, s63
	s_addc_u32 s1, s53, 0
	global_load_lds_dwordx4 v[0:1], off
	s_add_i32 m0, s57, 0x1c000
	v_lshl_add_u64 v[0:1], s[0:1], 0, v[24:25]
	global_load_lds_dwordx4 v[0:1], off
	v_lshl_add_u64 v[0:1], s[0:1], 0, v[146:147]
	s_add_i32 m0, s57, 0x1e000
	s_cmpk_lt_u32 s42, 0x100
	global_load_lds_dwordx4 v[0:1], off
	v_lshlrev_b32_e32 v0, 15, v8
	v_and_b32_e32 v0, 0xffff0000, v0
	v_lshl_add_u32 v0, v9, 12, v0
	v_and_b32_e32 v1, 1, v8
	v_lshl_or_b32 v0, v1, 6, v0
	v_lshl_add_u32 v148, v10, 1, v0
	v_lshlrev_b32_e32 v0, 15, v11
	v_and_b32_e32 v0, 0xffff0000, v0
	s_waitcnt vmcnt(6)
	v_lshl_add_u32 v0, v12, 12, v0
	v_and_b32_e32 v1, 1, v11
	v_lshl_or_b32 v0, v1, 6, v0
	s_cselect_b64 s[42:43], -1, 0
	v_or_b32_e32 v165, s39, v15
	v_mov_b32_e32 v149, v25
	v_lshl_add_u32 v150, v13, 1, v0
	v_mov_b32_e32 v151, v25
	s_mov_b32 s64, 0
	v_add_u32_e32 v166, 0, v17
	s_barrier
	s_branch .LBB0_1264

; __global__ void __launch_bounds__(512, 2) hymba_fwd(Params p) {
;     extern __shared__ __attribute__((aligned(16))) unsigned char lds_raw[];
	.amdhsa_kernel _Z9hymba_fwd6Params
		.amdhsa_group_segment_fixed_size 0
		.amdhsa_private_segment_fixed_size 0
		.amdhsa_kernarg_size 456
		.amdhsa_user_sgpr_count 2
		.amdhsa_user_sgpr_dispatch_ptr 0
		.amdhsa_user_sgpr_queue_ptr 0
		.amdhsa_user_sgpr_kernarg_segment_ptr 1
		.amdhsa_user_sgpr_dispatch_id 0
		.amdhsa_user_sgpr_kernarg_preload_length 0
		.amdhsa_user_sgpr_kernarg_preload_offset 0
		.amdhsa_user_sgpr_private_segment_size 0
		.amdhsa_uses_dynamic_stack 0
		.amdhsa_enable_private_segment 0
		.amdhsa_system_sgpr_workgroup_id_x 1
		.amdhsa_system_sgpr_workgroup_id_y 0
		.amdhsa_system_sgpr_workgroup_id_z 0
		.amdhsa_system_sgpr_workgroup_info 0
		.amdhsa_system_vgpr_workitem_id 2
		.amdhsa_next_free_vgpr 256
		.amdhsa_next_free_sgpr 102
		.amdhsa_accum_offset 256
		.amdhsa_reserve_vcc 1
		.amdhsa_float_round_mode_32 0
		.amdhsa_float_round_mode_16_64 0
		.amdhsa_float_denorm_mode_32 3
		.amdhsa_float_denorm_mode_16_64 3
		.amdhsa_dx10_clamp 1
		.amdhsa_ieee_mode 1
		.amdhsa_fp16_overflow 0
		.amdhsa_tg_split 0
		.amdhsa_exception_fp_ieee_invalid_op 0
		.amdhsa_exception_fp_denorm_src 0
		.amdhsa_exception_fp_ieee_div_zero 0
		.amdhsa_exception_fp_ieee_overflow 0
		.amdhsa_exception_fp_ieee_underflow 0
		.amdhsa_exception_fp_ieee_inexact 0
		.amdhsa_exception_int_div_zero 0
	.end_amdhsa_kernel

; __global__ void __launch_bounds__(512, 2) hymba_fwd(Params p) {
;     extern __shared__ __attribute__((aligned(16))) unsigned char lds_raw[];
amdhsa.kernels:
  - .agpr_count:     0
    .args:
      - .offset:         0
        .size:           200
        .value_kind:     by_value
      - .offset:         200
        .size:           4
        .value_kind:     hidden_block_count_x
      - .offset:         204
        .size:           4
        .value_kind:     hidden_block_count_y
      - .offset:         208
        .size:           4
        .value_kind:     hidden_block_count_z
      - .offset:         212
        .size:           2
        .value_kind:     hidden_group_size_x
      - .offset:         214
        .size:           2
        .value_kind:     hidden_group_size_y
      - .offset:         216
        .size:           2
        .value_kind:     hidden_group_size_z
      - .offset:         218
        .size:           2
        .value_kind:     hidden_remainder_x
      - .offset:         220
        .size:           2
        .value_kind:     hidden_remainder_y
      - .offset:         222
        .size:           2
        .value_kind:     hidden_remainder_z
      - .offset:         240
        .size:           8
        .value_kind:     hidden_global_offset_x
      - .offset:         248
        .size:           8
        .value_kind:     hidden_global_offset_y
      - .offset:         256
        .size:           8
        .value_kind:     hidden_global_offset_z
      - .offset:         264
        .size:           2
        .value_kind:     hidden_grid_dims
      - .offset:         288
        .size:           8
        .value_kind:     hidden_multigrid_sync_arg
      - .offset:         320
        .size:           4
        .value_kind:     hidden_dynamic_lds_size
    .group_segment_fixed_size: 0
    .kernarg_segment_align: 8
    .kernarg_segment_size: 456
    .language:       OpenCL C
    .language_version:
      - 2
      - 0
    .max_flat_workgroup_size: 512
    .name:           _Z9hymba_fwd6Params
    .private_segment_fixed_size: 0
    .sgpr_count:     108
    .sgpr_spill_count: 146
    .symbol:         _Z9hymba_fwd6Params.kd
    .uniform_work_group_size: 1
    .uses_dynamic_stack: false
    .vgpr_count:     256
    .vgpr_spill_count: 0
    .wavefront_size: 64
